# v36 + the 9 K-loop heads aligned to 64 bytes (s_nop padding, code placement section 9.3)
# baseline (speedup 1.0000x reference)
; template <class Epi, class Sched, bool ALIGN_EPI>
; __device__ __forceinline__ void gemm_phase(LAS unsigned char* lds, const Gemm g, const Sched& S, const Epi& E) {
;     ...
;         const bool has_next = S.next(ui + 1, nxt);
;         const char* nA = has_next ? (const char*)g.A + (size_t)nxt.pm * tstepA + (size_t)nxt.pn * g.a_koff * 2 : cA; const char* nB = has_next ? (const char*)g.Bt + (size_t)nxt.pn * tstepB : cB;
; #pragma unroll 1
;         for (int t = 0; t < nt; t += 2) {
;             const bool last = (t == nt - 2);
;             const char* a1 = cA + (size_t)(t + 1) * kstep;
;             const char* a2 = last ? nA : cA + (size_t)(t + 2) * kstep; const char* b2 = last ? nB : cB + (size_t)(t + 2) * kstep;
;             const char* a3 = a2 + kstep; const char* b3 = b2 + kstep;
;             PG8_LDB(B0, 0, 0); PG8_LDB(B1, 0, 1); PG8_SCHED; PG8_LDA(At, 0, 0); PG8_STAGE(PG8_SA(1, 1), a1 + hstepA, voffA);
;             PG8_WAIT_V(8); PG8_WAIT_L(0); PG8_BAR; PG8_MMA(0, 0, At, B0); PG8_MMA(0, 1, At, B1); PG8_BAR; PG8_SCHED;
;             PG8_LDA(At, 0, 1); PG8_STAGE(PG8_SB(0, 0), b2, voffB); PG8_STAGE(PG8_SB(0, 1), b2 + hstepB, voffB); PG8_STAGE(PG8_SA(0, 0), a2, voffA);
;             PG8_WAIT_V(8); PG8_WAIT_L(0); PG8_BAR; PG8_MMA(1, 0, At, B0); PG8_MMA(1, 1, At, B1); PG8_BAR; PG8_SCHED;
;             PG8_LDB(B0, 1, 0); PG8_LDB(B1, 1, 1); PG8_SCHED; PG8_LDA(At, 1, 0); PG8_STAGE(PG8_SA(0, 1), a2 + hstepA, voffA);
;             PG8_WAIT_V(8); PG8_WAIT_L(0); PG8_BAR; PG8_MMA(0, 0, At, B0); PG8_MMA(0, 1, At, B1); PG8_BAR; PG8_SCHED;
;             PG8_LDA(At, 1, 1); PG8_STAGE(PG8_SB(1, 0), b3, voffB); PG8_STAGE(PG8_SB(1, 1), b3 + hstepB, voffB); PG8_STAGE(PG8_SA(1, 0), a3, voffA);
;             PG8_WAIT_V(8); PG8_WAIT_L(0); PG8_BAR; PG8_MMA(1, 0, At, B0); PG8_MMA(1, 1, At, B1); PG8_BAR; PG8_SCHED;
;         }
;         if constexpr (ALIGN_EPI) { if (wr == 0) PG8_BAR; }
;         if constexpr (Epi::NPRE > 0) E(acc, cur, wr, wc, fr, fq, pre); else
;         if constexpr (!Epi::AFTER_DRAIN) E(acc, cur, wr, wc, fr, fq);
;         if (!has_next) break;
; #pragma unroll
;         for (int a = 0; a < 2; ++a)
; #pragma unroll
;             for (int b = 0; b < 2; ++b)
; #pragma unroll
;                 for (int m = 0; m < 4; ++m)
; #pragma unroll
;                     for (int n = 0; n < 2; ++n) acc[a][b][m][n] = (f32x4){0.f, 0.f, 0.f, 0.f};
.LBB0_112:
	s_mov_b32 s38, s41
	s_mov_b32 s40, s39
	s_ashr_i32 s39, s41, 31
	s_lshl_b64 s[8:9], s[38:39], 20
	s_add_u32 s42, s53, s8
	s_addc_u32 s43, s54, s9
	s_and_b64 s[8:9], s[46:47], exec
	s_cselect_b32 s24, s43, s5
	s_cselect_b32 s39, s42, s4
	s_ashr_i32 s41, s40, 31
	s_lshl_b64 s[8:9], s[40:41], 20
	s_add_u32 s44, s55, s8
	s_addc_u32 s45, s57, s9
	s_and_b64 s[8:9], s[46:47], exec
	s_cselect_b32 s41, s45, s7
	s_cselect_b32 s58, s44, s6
	s_add_u32 s59, s6, 0x100
	v_mov_b32_e32 v2, 0
	s_addc_u32 s80, s7, 0
	s_mov_b32 s81, -2
	v_mov_b32_e32 v3, v2
	v_mov_b32_e32 v4, v2
	v_mov_b32_e32 v5, v2
	v_mov_b32_e32 v6, v2
	v_mov_b32_e32 v7, v2
	v_mov_b32_e32 v8, v2
	v_mov_b32_e32 v9, v2
	v_mov_b32_e32 v18, v2
	v_mov_b32_e32 v19, v2
	v_mov_b32_e32 v20, v2
	v_mov_b32_e32 v21, v2
	v_mov_b32_e32 v22, v2
	v_mov_b32_e32 v23, v2
	v_mov_b32_e32 v24, v2
	v_mov_b32_e32 v25, v2
	v_mov_b32_e32 v34, v2
	v_mov_b32_e32 v35, v2
	v_mov_b32_e32 v36, v2
	v_mov_b32_e32 v37, v2
	v_mov_b32_e32 v38, v2
	v_mov_b32_e32 v39, v2
	v_mov_b32_e32 v40, v2
	v_mov_b32_e32 v41, v2
	v_mov_b32_e32 v50, v2
	v_mov_b32_e32 v51, v2
	v_mov_b32_e32 v52, v2
	v_mov_b32_e32 v53, v2
	v_mov_b32_e32 v54, v2
	v_mov_b32_e32 v55, v2
	v_mov_b32_e32 v56, v2
	v_mov_b32_e32 v57, v2
	v_mov_b32_e32 v10, v2
	v_mov_b32_e32 v11, v2
	v_mov_b32_e32 v12, v2
	v_mov_b32_e32 v13, v2
	v_mov_b32_e32 v14, v2
	v_mov_b32_e32 v15, v2
	v_mov_b32_e32 v16, v2
	v_mov_b32_e32 v17, v2
	v_mov_b32_e32 v26, v2
	v_mov_b32_e32 v27, v2
	v_mov_b32_e32 v28, v2
	v_mov_b32_e32 v29, v2
	v_mov_b32_e32 v30, v2
	v_mov_b32_e32 v31, v2
	v_mov_b32_e32 v32, v2
	v_mov_b32_e32 v33, v2
	v_mov_b32_e32 v42, v2
	v_mov_b32_e32 v43, v2
	v_mov_b32_e32 v44, v2
	v_mov_b32_e32 v45, v2
	v_mov_b32_e32 v46, v2
	v_mov_b32_e32 v47, v2
	v_mov_b32_e32 v48, v2
	v_mov_b32_e32 v49, v2
	v_mov_b32_e32 v58, v2
	v_mov_b32_e32 v59, v2
	v_mov_b32_e32 v60, v2
	v_mov_b32_e32 v61, v2
	v_mov_b32_e32 v62, v2
	v_mov_b32_e32 v63, v2
	v_mov_b32_e32 v64, v2
	v_mov_b32_e32 v65, v2
	v_mov_b32_e32 v66, v2
	v_mov_b32_e32 v67, v2
	v_mov_b32_e32 v68, v2
	v_mov_b32_e32 v69, v2
	v_mov_b32_e32 v70, v2
	v_mov_b32_e32 v71, v2
	v_mov_b32_e32 v72, v2
	v_mov_b32_e32 v73, v2
	v_mov_b32_e32 v82, v2
	v_mov_b32_e32 v83, v2
	v_mov_b32_e32 v84, v2
	v_mov_b32_e32 v85, v2
	v_mov_b32_e32 v86, v2
	v_mov_b32_e32 v87, v2
	v_mov_b32_e32 v88, v2
	v_mov_b32_e32 v89, v2
	v_mov_b32_e32 v98, v2
	v_mov_b32_e32 v99, v2
	v_mov_b32_e32 v100, v2
	v_mov_b32_e32 v101, v2
	v_mov_b32_e32 v102, v2
	v_mov_b32_e32 v103, v2
	v_mov_b32_e32 v104, v2
	v_mov_b32_e32 v105, v2
	v_mov_b32_e32 v114, v2
	v_mov_b32_e32 v115, v2
	v_mov_b32_e32 v116, v2
	v_mov_b32_e32 v117, v2
	v_mov_b32_e32 v118, v2
	v_mov_b32_e32 v119, v2
	v_mov_b32_e32 v120, v2
	v_mov_b32_e32 v121, v2
	v_mov_b32_e32 v74, v2
	v_mov_b32_e32 v75, v2
	v_mov_b32_e32 v76, v2
	v_mov_b32_e32 v77, v2
	v_mov_b32_e32 v78, v2
	v_mov_b32_e32 v79, v2
	v_mov_b32_e32 v80, v2
	v_mov_b32_e32 v81, v2
	v_mov_b32_e32 v90, v2
	v_mov_b32_e32 v91, v2
	v_mov_b32_e32 v92, v2
	v_mov_b32_e32 v93, v2
	v_mov_b32_e32 v94, v2
	v_mov_b32_e32 v95, v2
	v_mov_b32_e32 v96, v2
	v_mov_b32_e32 v97, v2
	v_mov_b32_e32 v106, v2
	v_mov_b32_e32 v107, v2
	v_mov_b32_e32 v108, v2
	v_mov_b32_e32 v109, v2
	v_mov_b32_e32 v110, v2
	v_mov_b32_e32 v111, v2
	v_mov_b32_e32 v112, v2
	v_mov_b32_e32 v113, v2
	v_mov_b32_e32 v122, v2
	v_mov_b32_e32 v123, v2
	v_mov_b32_e32 v124, v2
	v_mov_b32_e32 v125, v2
	v_mov_b32_e32 v126, v2
	v_mov_b32_e32 v127, v2
	v_mov_b32_e32 v128, v2
	v_mov_b32_e32 v129, v2
	.p2alignl 6, 3212836864

; template <class Epi, class Sched, bool ALIGN_EPI>
; __device__ __forceinline__ void gemm_phase(LAS unsigned char* lds, const Gemm g, const Sched& S, const Epi& E) {
;     ...
;         const bool has_next = S.next(ui + 1, nxt);
;         const char* nA = has_next ? (const char*)g.A + (size_t)nxt.pm * tstepA + (size_t)nxt.pn * g.a_koff * 2 : cA; const char* nB = has_next ? (const char*)g.Bt + (size_t)nxt.pn * tstepB : cB;
; #pragma unroll 1
;         for (int t = 0; t < nt; t += 2) {
;             const bool last = (t == nt - 2);
;             const char* a1 = cA + (size_t)(t + 1) * kstep;
;             const char* a2 = last ? nA : cA + (size_t)(t + 2) * kstep; const char* b2 = last ? nB : cB + (size_t)(t + 2) * kstep;
;             const char* a3 = a2 + kstep; const char* b3 = b2 + kstep;
;             PG8_LDB(B0, 0, 0); PG8_LDB(B1, 0, 1); PG8_SCHED; PG8_LDA(At, 0, 0); PG8_STAGE(PG8_SA(1, 1), a1 + hstepA, voffA);
;             PG8_WAIT_V(8); PG8_WAIT_L(0); PG8_BAR; PG8_MMA(0, 0, At, B0); PG8_MMA(0, 1, At, B1); PG8_BAR; PG8_SCHED;
;             PG8_LDA(At, 0, 1); PG8_STAGE(PG8_SB(0, 0), b2, voffB); PG8_STAGE(PG8_SB(0, 1), b2 + hstepB, voffB); PG8_STAGE(PG8_SA(0, 0), a2, voffA);
;             PG8_WAIT_V(8); PG8_WAIT_L(0); PG8_BAR; PG8_MMA(1, 0, At, B0); PG8_MMA(1, 1, At, B1); PG8_BAR; PG8_SCHED;
;             PG8_LDB(B0, 1, 0); PG8_LDB(B1, 1, 1); PG8_SCHED; PG8_LDA(At, 1, 0); PG8_STAGE(PG8_SA(0, 1), a2 + hstepA, voffA);
;             PG8_WAIT_V(8); PG8_WAIT_L(0); PG8_BAR; PG8_MMA(0, 0, At, B0); PG8_MMA(0, 1, At, B1); PG8_BAR; PG8_SCHED;
;             PG8_LDA(At, 1, 1); PG8_STAGE(PG8_SB(1, 0), b3, voffB); PG8_STAGE(PG8_SB(1, 1), b3 + hstepB, voffB); PG8_STAGE(PG8_SA(1, 0), a3, voffA);
;             PG8_WAIT_V(8); PG8_WAIT_L(0); PG8_BAR; PG8_MMA(1, 0, At, B0); PG8_MMA(1, 1, At, B1); PG8_BAR; PG8_SCHED;
;         }
;         if constexpr (ALIGN_EPI) { if (wr == 0) PG8_BAR; }
;         if constexpr (Epi::NPRE > 0) E(acc, cur, wr, wc, fr, fq, pre); else
;         if constexpr (!Epi::AFTER_DRAIN) E(acc, cur, wr, wc, fr, fq);
;         if (!has_next) break;
; #pragma unroll
;         for (int a = 0; a < 2; ++a)
; #pragma unroll
;             for (int b = 0; b < 2; ++b)
; #pragma unroll
;                 for (int m = 0; m < 4; ++m)
; #pragma unroll
;                     for (int n = 0; n < 2; ++n) acc[a][b][m][n] = (f32x4){0.f, 0.f, 0.f, 0.f};
.LBB0_804:
	s_ashr_i32 s17, s16, 31
	s_lshl_b64 s[18:19], s[16:17], 19
	s_add_u32 s3, s23, s18
	s_addc_u32 s17, s24, s19
	s_ashr_i32 s15, s14, 31
	s_lshl_b64 s[18:19], s[14:15], 9
	s_add_u32 s18, s3, s18
	s_addc_u32 s19, s17, s19
	s_and_b64 s[26:27], s[6:7], exec
	s_cselect_b32 s3, s19, s35
	s_cselect_b32 s17, s18, s34
	s_lshl_b64 s[26:27], s[14:15], 17
	s_add_u32 s26, s25, s26
	s_addc_u32 s27, s54, s27
	s_and_b64 s[36:37], s[6:7], exec
	v_mov_b32_e32 v2, 0
	s_cselect_b32 s15, s27, s31
	s_cselect_b32 s72, s26, s30
	s_mov_b64 s[40:41], 0
	s_mov_b64 s[36:37], -1
	s_mov_b64 s[38:39], 0
	v_mov_b32_e32 v3, v2
	v_mov_b32_e32 v4, v2
	v_mov_b32_e32 v5, v2
	v_mov_b32_e32 v6, v2
	v_mov_b32_e32 v7, v2
	v_mov_b32_e32 v8, v2
	v_mov_b32_e32 v9, v2
	v_mov_b32_e32 v10, v2
	v_mov_b32_e32 v11, v2
	v_mov_b32_e32 v12, v2
	v_mov_b32_e32 v13, v2
	v_mov_b32_e32 v14, v2
	v_mov_b32_e32 v15, v2
	v_mov_b32_e32 v16, v2
	v_mov_b32_e32 v17, v2
	v_mov_b32_e32 v18, v2
	v_mov_b32_e32 v19, v2
	v_mov_b32_e32 v20, v2
	v_mov_b32_e32 v21, v2
	v_mov_b32_e32 v22, v2
	v_mov_b32_e32 v23, v2
	v_mov_b32_e32 v24, v2
	v_mov_b32_e32 v25, v2
	v_mov_b32_e32 v26, v2
	v_mov_b32_e32 v27, v2
	v_mov_b32_e32 v28, v2
	v_mov_b32_e32 v29, v2
	v_mov_b32_e32 v30, v2
	v_mov_b32_e32 v31, v2
	v_mov_b32_e32 v32, v2
	v_mov_b32_e32 v33, v2
	v_mov_b32_e32 v54, v2
	v_mov_b32_e32 v55, v2
	v_mov_b32_e32 v56, v2
	v_mov_b32_e32 v57, v2
	v_mov_b32_e32 v62, v2
	v_mov_b32_e32 v63, v2
	v_mov_b32_e32 v64, v2
	v_mov_b32_e32 v65, v2
	v_mov_b32_e32 v74, v2
	v_mov_b32_e32 v75, v2
	v_mov_b32_e32 v76, v2
	v_mov_b32_e32 v77, v2
	v_mov_b32_e32 v78, v2
	v_mov_b32_e32 v79, v2
	v_mov_b32_e32 v80, v2
	v_mov_b32_e32 v81, v2
	v_mov_b32_e32 v82, v2
	v_mov_b32_e32 v83, v2
	v_mov_b32_e32 v84, v2
	v_mov_b32_e32 v85, v2
	v_mov_b32_e32 v86, v2
	v_mov_b32_e32 v87, v2
	v_mov_b32_e32 v88, v2
	v_mov_b32_e32 v89, v2
	v_mov_b32_e32 v90, v2
	v_mov_b32_e32 v91, v2
	v_mov_b32_e32 v92, v2
	v_mov_b32_e32 v93, v2
	v_mov_b32_e32 v94, v2
	v_mov_b32_e32 v95, v2
	v_mov_b32_e32 v96, v2
	v_mov_b32_e32 v97, v2
	v_mov_b32_e32 v34, v2
	v_mov_b32_e32 v35, v2
	v_mov_b32_e32 v36, v2
	v_mov_b32_e32 v37, v2
	v_mov_b32_e32 v38, v2
	v_mov_b32_e32 v39, v2
	v_mov_b32_e32 v40, v2
	v_mov_b32_e32 v41, v2
	v_mov_b32_e32 v42, v2
	v_mov_b32_e32 v43, v2
	v_mov_b32_e32 v44, v2
	v_mov_b32_e32 v45, v2
	v_mov_b32_e32 v46, v2
	v_mov_b32_e32 v47, v2
	v_mov_b32_e32 v48, v2
	v_mov_b32_e32 v49, v2
	v_mov_b32_e32 v50, v2
	v_mov_b32_e32 v51, v2
	v_mov_b32_e32 v52, v2
	v_mov_b32_e32 v53, v2
	v_mov_b32_e32 v58, v2
	v_mov_b32_e32 v59, v2
	v_mov_b32_e32 v60, v2
	v_mov_b32_e32 v61, v2
	v_mov_b32_e32 v66, v2
	v_mov_b32_e32 v67, v2
	v_mov_b32_e32 v68, v2
	v_mov_b32_e32 v69, v2
	v_mov_b32_e32 v70, v2
	v_mov_b32_e32 v71, v2
	v_mov_b32_e32 v72, v2
	v_mov_b32_e32 v73, v2
	v_mov_b32_e32 v98, v2
	v_mov_b32_e32 v99, v2
	v_mov_b32_e32 v100, v2
	v_mov_b32_e32 v101, v2
	v_mov_b32_e32 v102, v2
	v_mov_b32_e32 v103, v2
	v_mov_b32_e32 v104, v2
	v_mov_b32_e32 v105, v2
	v_mov_b32_e32 v106, v2
	v_mov_b32_e32 v107, v2
	v_mov_b32_e32 v108, v2
	v_mov_b32_e32 v109, v2
	v_mov_b32_e32 v110, v2
	v_mov_b32_e32 v111, v2
	v_mov_b32_e32 v112, v2
	v_mov_b32_e32 v113, v2
	v_mov_b32_e32 v114, v2
	v_mov_b32_e32 v115, v2
	v_mov_b32_e32 v116, v2
	v_mov_b32_e32 v117, v2
	v_mov_b32_e32 v118, v2
	v_mov_b32_e32 v119, v2
	v_mov_b32_e32 v120, v2
	v_mov_b32_e32 v121, v2
	v_mov_b32_e32 v122, v2
	v_mov_b32_e32 v123, v2
	v_mov_b32_e32 v124, v2
	v_mov_b32_e32 v125, v2
	v_mov_b32_e32 v126, v2
	v_mov_b32_e32 v127, v2
	v_mov_b32_e32 v128, v2
	v_mov_b32_e32 v129, v2
	.p2alignl 6, 3212836864

; template <class Epi, class Sched, bool ALIGN_EPI>
; __device__ __forceinline__ void gemm_phase(LAS unsigned char* lds, const Gemm g, const Sched& S, const Epi& E) {
;     ...
;         const bool has_next = S.next(ui + 1, nxt);
;         const char* nA = has_next ? (const char*)g.A + (size_t)nxt.pm * tstepA + (size_t)nxt.pn * g.a_koff * 2 : cA; const char* nB = has_next ? (const char*)g.Bt + (size_t)nxt.pn * tstepB : cB;
; #pragma unroll 1
;         for (int t = 0; t < nt; t += 2) {
;             const bool last = (t == nt - 2);
;             const char* a1 = cA + (size_t)(t + 1) * kstep;
;             const char* a2 = last ? nA : cA + (size_t)(t + 2) * kstep; const char* b2 = last ? nB : cB + (size_t)(t + 2) * kstep;
;             const char* a3 = a2 + kstep; const char* b3 = b2 + kstep;
;             PG8_LDB(B0, 0, 0); PG8_LDB(B1, 0, 1); PG8_SCHED; PG8_LDA(At, 0, 0); PG8_STAGE(PG8_SA(1, 1), a1 + hstepA, voffA);
;             PG8_WAIT_V(8); PG8_WAIT_L(0); PG8_BAR; PG8_MMA(0, 0, At, B0); PG8_MMA(0, 1, At, B1); PG8_BAR; PG8_SCHED;
;             PG8_LDA(At, 0, 1); PG8_STAGE(PG8_SB(0, 0), b2, voffB); PG8_STAGE(PG8_SB(0, 1), b2 + hstepB, voffB); PG8_STAGE(PG8_SA(0, 0), a2, voffA);
;             PG8_WAIT_V(8); PG8_WAIT_L(0); PG8_BAR; PG8_MMA(1, 0, At, B0); PG8_MMA(1, 1, At, B1); PG8_BAR; PG8_SCHED;
;             PG8_LDB(B0, 1, 0); PG8_LDB(B1, 1, 1); PG8_SCHED; PG8_LDA(At, 1, 0); PG8_STAGE(PG8_SA(0, 1), a2 + hstepA, voffA);
;             PG8_WAIT_V(8); PG8_WAIT_L(0); PG8_BAR; PG8_MMA(0, 0, At, B0); PG8_MMA(0, 1, At, B1); PG8_BAR; PG8_SCHED;
;             PG8_LDA(At, 1, 1); PG8_STAGE(PG8_SB(1, 0), b3, voffB); PG8_STAGE(PG8_SB(1, 1), b3 + hstepB, voffB); PG8_STAGE(PG8_SA(1, 0), a3, voffA);
;             PG8_WAIT_V(8); PG8_WAIT_L(0); PG8_BAR; PG8_MMA(1, 0, At, B0); PG8_MMA(1, 1, At, B1); PG8_BAR; PG8_SCHED;
;         }
;         if constexpr (ALIGN_EPI) { if (wr == 0) PG8_BAR; }
;         if constexpr (Epi::NPRE > 0) E(acc, cur, wr, wc, fr, fq, pre); else
;         if constexpr (!Epi::AFTER_DRAIN) E(acc, cur, wr, wc, fr, fq);
;         if (!has_next) break;
; #pragma unroll
;         for (int a = 0; a < 2; ++a)
; #pragma unroll
;             for (int b = 0; b < 2; ++b)
; #pragma unroll
;                 for (int m = 0; m < 4; ++m)
; #pragma unroll
;                     for (int n = 0; n < 2; ++n) acc[a][b][m][n] = (f32x4){0.f, 0.f, 0.f, 0.f};
.LBB0_1136:
	s_ashr_i32 s27, s26, 31
	s_lshl_b64 s[6:7], s[26:27], 20
	s_add_u32 s28, s23, s6
	s_addc_u32 s29, s24, s7
	s_and_b64 s[6:7], s[12:13], exec
	s_cselect_b32 s3, s29, s37
	s_cselect_b32 s5, s28, s36
	s_ashr_i32 s19, s18, 31
	s_lshl_b64 s[6:7], s[18:19], 20
	s_add_u32 s30, s25, s6
	s_addc_u32 s31, s42, s7
	s_and_b64 s[6:7], s[12:13], exec
	s_cselect_b32 s6, s31, s35
	s_cselect_b32 s7, s30, s34
	s_add_u32 s19, s36, 0x100
	s_addc_u32 s27, s37, 0
	s_add_u32 s61, s34, 0x100
	s_addc_u32 s62, s35, 0
	s_add_u32 s34, s36, 0x80080
	v_mov_b32_e32 v2, 0
	s_addc_u32 s35, s37, 0
	s_mov_b32 s63, -2
	s_waitcnt lgkmcnt(0)
	v_mov_b32_e32 v3, v2
	v_mov_b32_e32 v4, v2
	v_mov_b32_e32 v5, v2
	v_mov_b32_e32 v6, v2
	v_mov_b32_e32 v7, v2
	v_mov_b32_e32 v8, v2
	v_mov_b32_e32 v9, v2
	v_mov_b32_e32 v18, v2
	v_mov_b32_e32 v19, v2
	v_mov_b32_e32 v20, v2
	v_mov_b32_e32 v21, v2
	v_mov_b32_e32 v22, v2
	v_mov_b32_e32 v23, v2
	v_mov_b32_e32 v24, v2
	v_mov_b32_e32 v25, v2
	v_mov_b32_e32 v34, v2
	v_mov_b32_e32 v35, v2
	v_mov_b32_e32 v36, v2
	v_mov_b32_e32 v37, v2
	v_mov_b32_e32 v38, v2
	v_mov_b32_e32 v39, v2
	v_mov_b32_e32 v40, v2
	v_mov_b32_e32 v41, v2
	v_mov_b32_e32 v50, v2
	v_mov_b32_e32 v51, v2
	v_mov_b32_e32 v52, v2
	v_mov_b32_e32 v53, v2
	v_mov_b32_e32 v54, v2
	v_mov_b32_e32 v55, v2
	v_mov_b32_e32 v56, v2
	v_mov_b32_e32 v57, v2
	v_mov_b32_e32 v10, v2
	v_mov_b32_e32 v11, v2
	v_mov_b32_e32 v12, v2
	v_mov_b32_e32 v13, v2
	v_mov_b32_e32 v14, v2
	v_mov_b32_e32 v15, v2
	v_mov_b32_e32 v16, v2
	v_mov_b32_e32 v17, v2
	v_mov_b32_e32 v26, v2
	v_mov_b32_e32 v27, v2
	v_mov_b32_e32 v28, v2
	v_mov_b32_e32 v29, v2
	v_mov_b32_e32 v30, v2
	v_mov_b32_e32 v31, v2
	v_mov_b32_e32 v32, v2
	v_mov_b32_e32 v33, v2
	v_mov_b32_e32 v42, v2
	v_mov_b32_e32 v43, v2
	v_mov_b32_e32 v44, v2
	v_mov_b32_e32 v45, v2
	v_mov_b32_e32 v46, v2
	v_mov_b32_e32 v47, v2
	v_mov_b32_e32 v48, v2
	v_mov_b32_e32 v49, v2
	v_mov_b32_e32 v58, v2
	v_mov_b32_e32 v59, v2
	v_mov_b32_e32 v60, v2
	v_mov_b32_e32 v61, v2
	v_mov_b32_e32 v62, v2
	v_mov_b32_e32 v63, v2
	v_mov_b32_e32 v64, v2
	v_mov_b32_e32 v65, v2
	v_mov_b32_e32 v66, v2
	v_mov_b32_e32 v67, v2
	v_mov_b32_e32 v68, v2
	v_mov_b32_e32 v69, v2
	v_mov_b32_e32 v70, v2
	v_mov_b32_e32 v71, v2
	v_mov_b32_e32 v72, v2
	v_mov_b32_e32 v73, v2
	v_mov_b32_e32 v82, v2
	v_mov_b32_e32 v83, v2
	v_mov_b32_e32 v84, v2
	v_mov_b32_e32 v85, v2
	v_mov_b32_e32 v86, v2
	v_mov_b32_e32 v87, v2
	v_mov_b32_e32 v88, v2
	v_mov_b32_e32 v89, v2
	v_mov_b32_e32 v98, v2
	v_mov_b32_e32 v99, v2
	v_mov_b32_e32 v100, v2
	v_mov_b32_e32 v101, v2
	v_mov_b32_e32 v102, v2
	v_mov_b32_e32 v103, v2
	v_mov_b32_e32 v104, v2
	v_mov_b32_e32 v105, v2
	v_mov_b32_e32 v118, v2
	v_mov_b32_e32 v119, v2
	v_mov_b32_e32 v120, v2
	v_mov_b32_e32 v121, v2
	v_mov_b32_e32 v122, v2
	v_mov_b32_e32 v123, v2
	v_mov_b32_e32 v124, v2
	v_mov_b32_e32 v125, v2
	v_mov_b32_e32 v74, v2
	v_mov_b32_e32 v75, v2
	v_mov_b32_e32 v76, v2
	v_mov_b32_e32 v77, v2
	v_mov_b32_e32 v78, v2
	v_mov_b32_e32 v79, v2
	v_mov_b32_e32 v80, v2
	v_mov_b32_e32 v81, v2
	v_mov_b32_e32 v90, v2
	v_mov_b32_e32 v91, v2
	v_mov_b32_e32 v92, v2
	v_mov_b32_e32 v93, v2
	v_mov_b32_e32 v94, v2
	v_mov_b32_e32 v95, v2
	v_mov_b32_e32 v96, v2
	v_mov_b32_e32 v97, v2
	v_mov_b32_e32 v106, v2
	v_mov_b32_e32 v107, v2
	v_mov_b32_e32 v108, v2
	v_mov_b32_e32 v109, v2
	v_mov_b32_e32 v114, v2
	v_mov_b32_e32 v115, v2
	v_mov_b32_e32 v116, v2
	v_mov_b32_e32 v117, v2
	s_waitcnt vmcnt(3)
	v_mov_b32_e32 v134, v2
	s_waitcnt vmcnt(0)
	v_mov_b32_e32 v135, v2
	v_mov_b32_e32 v136, v2
	v_mov_b32_e32 v137, v2
	v_mov_b32_e32 v138, v2
	v_mov_b32_e32 v139, v2
	v_mov_b32_e32 v140, v2
	v_mov_b32_e32 v141, v2
	.p2alignl 6, 3212836864

; template <class Epi, class Sched, bool ALIGN_EPI>
; __device__ __forceinline__ void gemm_phase(LAS unsigned char* lds, const Gemm g, const Sched& S, const Epi& E) {
;     ...
;         const bool has_next = S.next(ui + 1, nxt);
;         const char* nA = has_next ? (const char*)g.A + (size_t)nxt.pm * tstepA + (size_t)nxt.pn * g.a_koff * 2 : cA; const char* nB = has_next ? (const char*)g.Bt + (size_t)nxt.pn * tstepB : cB;
; #pragma unroll 1
;         for (int t = 0; t < nt; t += 2) {
;             const bool last = (t == nt - 2);
;             const char* a1 = cA + (size_t)(t + 1) * kstep;
;             const char* a2 = last ? nA : cA + (size_t)(t + 2) * kstep; const char* b2 = last ? nB : cB + (size_t)(t + 2) * kstep;
;             const char* a3 = a2 + kstep; const char* b3 = b2 + kstep;
;             PG8_LDB(B0, 0, 0); PG8_LDB(B1, 0, 1); PG8_SCHED; PG8_LDA(At, 0, 0); PG8_STAGE(PG8_SA(1, 1), a1 + hstepA, voffA);
;             PG8_WAIT_V(8); PG8_WAIT_L(0); PG8_BAR; PG8_MMA(0, 0, At, B0); PG8_MMA(0, 1, At, B1); PG8_BAR; PG8_SCHED;
;             PG8_LDA(At, 0, 1); PG8_STAGE(PG8_SB(0, 0), b2, voffB); PG8_STAGE(PG8_SB(0, 1), b2 + hstepB, voffB); PG8_STAGE(PG8_SA(0, 0), a2, voffA);
;             PG8_WAIT_V(8); PG8_WAIT_L(0); PG8_BAR; PG8_MMA(1, 0, At, B0); PG8_MMA(1, 1, At, B1); PG8_BAR; PG8_SCHED;
;             PG8_LDB(B0, 1, 0); PG8_LDB(B1, 1, 1); PG8_SCHED; PG8_LDA(At, 1, 0); PG8_STAGE(PG8_SA(0, 1), a2 + hstepA, voffA);
;             PG8_WAIT_V(8); PG8_WAIT_L(0); PG8_BAR; PG8_MMA(0, 0, At, B0); PG8_MMA(0, 1, At, B1); PG8_BAR; PG8_SCHED;
;             PG8_LDA(At, 1, 1); PG8_STAGE(PG8_SB(1, 0), b3, voffB); PG8_STAGE(PG8_SB(1, 1), b3 + hstepB, voffB); PG8_STAGE(PG8_SA(1, 0), a3, voffA);
;             PG8_WAIT_V(8); PG8_WAIT_L(0); PG8_BAR; PG8_MMA(1, 0, At, B0); PG8_MMA(1, 1, At, B1); PG8_BAR; PG8_SCHED;
;         }
;         if constexpr (ALIGN_EPI) { if (wr == 0) PG8_BAR; }
;         if constexpr (Epi::NPRE > 0) E(acc, cur, wr, wc, fr, fq, pre); else
;         if constexpr (!Epi::AFTER_DRAIN) E(acc, cur, wr, wc, fr, fq);
;         if (!has_next) break;
; #pragma unroll
;         for (int a = 0; a < 2; ++a)
; #pragma unroll
;             for (int b = 0; b < 2; ++b)
; #pragma unroll
;                 for (int m = 0; m < 4; ++m)
; #pragma unroll
;                     for (int n = 0; n < 2; ++n) acc[a][b][m][n] = (f32x4){0.f, 0.f, 0.f, 0.f};
.LBB0_1217:
	s_ashr_i32 s27, s26, 31
	s_lshl_b64 s[6:7], s[26:27], 20
	s_add_u32 s28, s23, s6
	s_addc_u32 s29, s24, s7
	s_and_b64 s[6:7], s[10:11], exec
	s_cselect_b32 s3, s29, s35
	s_cselect_b32 s5, s28, s34
	s_ashr_i32 s19, s18, 31
	s_lshl_b64 s[6:7], s[18:19], 20
	s_add_u32 s30, s25, s6
	s_addc_u32 s31, s44, s7
	s_and_b64 s[6:7], s[10:11], exec
	s_cselect_b32 s6, s31, s37
	s_cselect_b32 s7, s30, s36
	s_add_u32 s19, s36, 0x100
	v_mov_b32_e32 v2, 0
	s_addc_u32 s27, s37, 0
	s_mov_b32 s64, -2
	v_mov_b32_e32 v3, v2
	v_mov_b32_e32 v4, v2
	v_mov_b32_e32 v5, v2
	v_mov_b32_e32 v6, v2
	v_mov_b32_e32 v7, v2
	v_mov_b32_e32 v8, v2
	v_mov_b32_e32 v9, v2
	v_mov_b32_e32 v18, v2
	v_mov_b32_e32 v19, v2
	v_mov_b32_e32 v20, v2
	v_mov_b32_e32 v21, v2
	v_mov_b32_e32 v22, v2
	v_mov_b32_e32 v23, v2
	v_mov_b32_e32 v24, v2
	v_mov_b32_e32 v25, v2
	v_mov_b32_e32 v34, v2
	v_mov_b32_e32 v35, v2
	v_mov_b32_e32 v36, v2
	v_mov_b32_e32 v37, v2
	v_mov_b32_e32 v38, v2
	v_mov_b32_e32 v39, v2
	v_mov_b32_e32 v40, v2
	v_mov_b32_e32 v41, v2
	v_mov_b32_e32 v50, v2
	v_mov_b32_e32 v51, v2
	v_mov_b32_e32 v52, v2
	v_mov_b32_e32 v53, v2
	v_mov_b32_e32 v54, v2
	v_mov_b32_e32 v55, v2
	v_mov_b32_e32 v56, v2
	v_mov_b32_e32 v57, v2
	v_mov_b32_e32 v10, v2
	v_mov_b32_e32 v11, v2
	v_mov_b32_e32 v12, v2
	v_mov_b32_e32 v13, v2
	v_mov_b32_e32 v14, v2
	v_mov_b32_e32 v15, v2
	v_mov_b32_e32 v16, v2
	v_mov_b32_e32 v17, v2
	v_mov_b32_e32 v26, v2
	v_mov_b32_e32 v27, v2
	v_mov_b32_e32 v28, v2
	v_mov_b32_e32 v29, v2
	v_mov_b32_e32 v30, v2
	v_mov_b32_e32 v31, v2
	v_mov_b32_e32 v32, v2
	v_mov_b32_e32 v33, v2
	v_mov_b32_e32 v42, v2
	v_mov_b32_e32 v43, v2
	v_mov_b32_e32 v44, v2
	v_mov_b32_e32 v45, v2
	v_mov_b32_e32 v46, v2
	v_mov_b32_e32 v47, v2
	v_mov_b32_e32 v48, v2
	v_mov_b32_e32 v49, v2
	v_mov_b32_e32 v58, v2
	v_mov_b32_e32 v59, v2
	v_mov_b32_e32 v60, v2
	v_mov_b32_e32 v61, v2
	v_mov_b32_e32 v62, v2
	v_mov_b32_e32 v63, v2
	v_mov_b32_e32 v64, v2
	v_mov_b32_e32 v65, v2
	v_mov_b32_e32 v66, v2
	v_mov_b32_e32 v67, v2
	v_mov_b32_e32 v68, v2
	v_mov_b32_e32 v69, v2
	v_mov_b32_e32 v70, v2
	v_mov_b32_e32 v71, v2
	v_mov_b32_e32 v72, v2
	v_mov_b32_e32 v73, v2
	v_mov_b32_e32 v82, v2
	v_mov_b32_e32 v83, v2
	v_mov_b32_e32 v84, v2
	v_mov_b32_e32 v85, v2
	v_mov_b32_e32 v86, v2
	v_mov_b32_e32 v87, v2
	v_mov_b32_e32 v88, v2
	v_mov_b32_e32 v89, v2
	v_mov_b32_e32 v98, v2
	v_mov_b32_e32 v99, v2
	v_mov_b32_e32 v100, v2
	v_mov_b32_e32 v101, v2
	v_mov_b32_e32 v102, v2
	v_mov_b32_e32 v103, v2
	v_mov_b32_e32 v104, v2
	v_mov_b32_e32 v105, v2
	v_mov_b32_e32 v114, v2
	v_mov_b32_e32 v115, v2
	v_mov_b32_e32 v116, v2
	v_mov_b32_e32 v117, v2
	v_mov_b32_e32 v118, v2
	v_mov_b32_e32 v119, v2
	v_mov_b32_e32 v120, v2
	v_mov_b32_e32 v121, v2
	v_mov_b32_e32 v74, v2
	v_mov_b32_e32 v75, v2
	v_mov_b32_e32 v76, v2
	v_mov_b32_e32 v77, v2
	v_mov_b32_e32 v78, v2
	v_mov_b32_e32 v79, v2
	v_mov_b32_e32 v80, v2
	v_mov_b32_e32 v81, v2
	v_mov_b32_e32 v90, v2
	v_mov_b32_e32 v91, v2
	v_mov_b32_e32 v92, v2
	v_mov_b32_e32 v93, v2
	v_mov_b32_e32 v94, v2
	v_mov_b32_e32 v95, v2
	v_mov_b32_e32 v96, v2
	v_mov_b32_e32 v97, v2
	v_mov_b32_e32 v106, v2
	v_mov_b32_e32 v107, v2
	v_mov_b32_e32 v108, v2
	v_mov_b32_e32 v109, v2
	v_mov_b32_e32 v110, v2
	v_mov_b32_e32 v111, v2
	v_mov_b32_e32 v112, v2
	v_mov_b32_e32 v113, v2
	v_mov_b32_e32 v122, v2
	v_mov_b32_e32 v123, v2
	v_mov_b32_e32 v124, v2
	v_mov_b32_e32 v125, v2
	v_mov_b32_e32 v126, v2
	v_mov_b32_e32 v127, v2
	v_mov_b32_e32 v128, v2
	v_mov_b32_e32 v129, v2
	.p2alignl 6, 3212836864

; template <class Epi, class Sched, bool ALIGN_EPI>
; __device__ __forceinline__ void gemm_phase(LAS unsigned char* lds, const Gemm g, const Sched& S, const Epi& E) {
;     ...
;         const bool has_next = S.next(ui + 1, nxt);
;         const char* nA = has_next ? (const char*)g.A + (size_t)nxt.pm * tstepA + (size_t)nxt.pn * g.a_koff * 2 : cA; const char* nB = has_next ? (const char*)g.Bt + (size_t)nxt.pn * tstepB : cB;
; #pragma unroll 1
;         for (int t = 0; t < nt; t += 2) {
;             const bool last = (t == nt - 2);
;             const char* a1 = cA + (size_t)(t + 1) * kstep;
;             const char* a2 = last ? nA : cA + (size_t)(t + 2) * kstep; const char* b2 = last ? nB : cB + (size_t)(t + 2) * kstep;
;             const char* a3 = a2 + kstep; const char* b3 = b2 + kstep;
;             PG8_LDB(B0, 0, 0); PG8_LDB(B1, 0, 1); PG8_SCHED; PG8_LDA(At, 0, 0); PG8_STAGE(PG8_SA(1, 1), a1 + hstepA, voffA);
;             PG8_WAIT_V(8); PG8_WAIT_L(0); PG8_BAR; PG8_MMA(0, 0, At, B0); PG8_MMA(0, 1, At, B1); PG8_BAR; PG8_SCHED;
;             PG8_LDA(At, 0, 1); PG8_STAGE(PG8_SB(0, 0), b2, voffB); PG8_STAGE(PG8_SB(0, 1), b2 + hstepB, voffB); PG8_STAGE(PG8_SA(0, 0), a2, voffA);
;             PG8_WAIT_V(8); PG8_WAIT_L(0); PG8_BAR; PG8_MMA(1, 0, At, B0); PG8_MMA(1, 1, At, B1); PG8_BAR; PG8_SCHED;
;             PG8_LDB(B0, 1, 0); PG8_LDB(B1, 1, 1); PG8_SCHED; PG8_LDA(At, 1, 0); PG8_STAGE(PG8_SA(0, 1), a2 + hstepA, voffA);
;             PG8_WAIT_V(8); PG8_WAIT_L(0); PG8_BAR; PG8_MMA(0, 0, At, B0); PG8_MMA(0, 1, At, B1); PG8_BAR; PG8_SCHED;
;             PG8_LDA(At, 1, 1); PG8_STAGE(PG8_SB(1, 0), b3, voffB); PG8_STAGE(PG8_SB(1, 1), b3 + hstepB, voffB); PG8_STAGE(PG8_SA(1, 0), a3, voffA);
;             PG8_WAIT_V(8); PG8_WAIT_L(0); PG8_BAR; PG8_MMA(1, 0, At, B0); PG8_MMA(1, 1, At, B1); PG8_BAR; PG8_SCHED;
;         }
;         if constexpr (ALIGN_EPI) { if (wr == 0) PG8_BAR; }
;         if constexpr (Epi::NPRE > 0) E(acc, cur, wr, wc, fr, fq, pre); else
;         if constexpr (!Epi::AFTER_DRAIN) E(acc, cur, wr, wc, fr, fq);
;         if (!has_next) break;
; #pragma unroll
;         for (int a = 0; a < 2; ++a)
; #pragma unroll
;             for (int b = 0; b < 2; ++b)
; #pragma unroll
;                 for (int m = 0; m < 4; ++m)
; #pragma unroll
;                     for (int n = 0; n < 2; ++n) acc[a][b][m][n] = (f32x4){0.f, 0.f, 0.f, 0.f};
.LBB0_1316:
	s_add_u32 s6, s28, 0x100
	s_addc_u32 s7, s29, 0
	s_add_u32 s56, s4, 0x100
	s_addc_u32 s57, s5, 0
	s_add_u32 s4, s28, 0x160080
	v_mov_b32_e32 v2, 0
	s_addc_u32 s5, s29, 0
	s_mov_b32 s58, -2
	s_waitcnt lgkmcnt(0)
	v_mov_b32_e32 v3, v2
	v_mov_b32_e32 v4, v2
	v_mov_b32_e32 v5, v2
	v_mov_b32_e32 v6, v2
	v_mov_b32_e32 v7, v2
	v_mov_b32_e32 v8, v2
	v_mov_b32_e32 v9, v2
	v_mov_b32_e32 v18, v2
	v_mov_b32_e32 v19, v2
	v_mov_b32_e32 v20, v2
	v_mov_b32_e32 v21, v2
	v_mov_b32_e32 v22, v2
	v_mov_b32_e32 v23, v2
	v_mov_b32_e32 v24, v2
	v_mov_b32_e32 v25, v2
	v_mov_b32_e32 v34, v2
	v_mov_b32_e32 v35, v2
	v_mov_b32_e32 v36, v2
	v_mov_b32_e32 v37, v2
	v_mov_b32_e32 v38, v2
	v_mov_b32_e32 v39, v2
	v_mov_b32_e32 v40, v2
	v_mov_b32_e32 v41, v2
	v_mov_b32_e32 v50, v2
	v_mov_b32_e32 v51, v2
	v_mov_b32_e32 v52, v2
	v_mov_b32_e32 v53, v2
	v_mov_b32_e32 v54, v2
	v_mov_b32_e32 v55, v2
	v_mov_b32_e32 v56, v2
	v_mov_b32_e32 v57, v2
	v_mov_b32_e32 v10, v2
	v_mov_b32_e32 v11, v2
	v_mov_b32_e32 v12, v2
	v_mov_b32_e32 v13, v2
	v_mov_b32_e32 v14, v2
	v_mov_b32_e32 v15, v2
	v_mov_b32_e32 v16, v2
	v_mov_b32_e32 v17, v2
	v_mov_b32_e32 v26, v2
	v_mov_b32_e32 v27, v2
	v_mov_b32_e32 v28, v2
	v_mov_b32_e32 v29, v2
	v_mov_b32_e32 v30, v2
	v_mov_b32_e32 v31, v2
	v_mov_b32_e32 v32, v2
	v_mov_b32_e32 v33, v2
	v_mov_b32_e32 v42, v2
	v_mov_b32_e32 v43, v2
	v_mov_b32_e32 v44, v2
	v_mov_b32_e32 v45, v2
	v_mov_b32_e32 v46, v2
	v_mov_b32_e32 v47, v2
	v_mov_b32_e32 v48, v2
	v_mov_b32_e32 v49, v2
	v_mov_b32_e32 v58, v2
	v_mov_b32_e32 v59, v2
	v_mov_b32_e32 v60, v2
	v_mov_b32_e32 v61, v2
	v_mov_b32_e32 v62, v2
	v_mov_b32_e32 v63, v2
	v_mov_b32_e32 v64, v2
	v_mov_b32_e32 v65, v2
	v_mov_b32_e32 v66, v2
	v_mov_b32_e32 v67, v2
	v_mov_b32_e32 v68, v2
	v_mov_b32_e32 v69, v2
	v_mov_b32_e32 v70, v2
	v_mov_b32_e32 v71, v2
	v_mov_b32_e32 v72, v2
	v_mov_b32_e32 v73, v2
	v_mov_b32_e32 v82, v2
	v_mov_b32_e32 v83, v2
	v_mov_b32_e32 v84, v2
	v_mov_b32_e32 v85, v2
	v_mov_b32_e32 v86, v2
	v_mov_b32_e32 v87, v2
	v_mov_b32_e32 v88, v2
	v_mov_b32_e32 v89, v2
	v_mov_b32_e32 v98, v2
	v_mov_b32_e32 v99, v2
	v_mov_b32_e32 v100, v2
	v_mov_b32_e32 v101, v2
	v_mov_b32_e32 v102, v2
	v_mov_b32_e32 v103, v2
	v_mov_b32_e32 v104, v2
	v_mov_b32_e32 v105, v2
	v_mov_b32_e32 v118, v2
	v_mov_b32_e32 v119, v2
	v_mov_b32_e32 v120, v2
	v_mov_b32_e32 v121, v2
	v_mov_b32_e32 v122, v2
	v_mov_b32_e32 v123, v2
	v_mov_b32_e32 v124, v2
	v_mov_b32_e32 v125, v2
	v_mov_b32_e32 v74, v2
	v_mov_b32_e32 v75, v2
	v_mov_b32_e32 v76, v2
	v_mov_b32_e32 v77, v2
	v_mov_b32_e32 v78, v2
	v_mov_b32_e32 v79, v2
	v_mov_b32_e32 v80, v2
	v_mov_b32_e32 v81, v2
	v_mov_b32_e32 v90, v2
	v_mov_b32_e32 v91, v2
	v_mov_b32_e32 v92, v2
	v_mov_b32_e32 v93, v2
	v_mov_b32_e32 v94, v2
	v_mov_b32_e32 v95, v2
	v_mov_b32_e32 v96, v2
	v_mov_b32_e32 v97, v2
	v_mov_b32_e32 v106, v2
	v_mov_b32_e32 v107, v2
	v_mov_b32_e32 v108, v2
	v_mov_b32_e32 v109, v2
	v_mov_b32_e32 v114, v2
	v_mov_b32_e32 v115, v2
	v_mov_b32_e32 v116, v2
	v_mov_b32_e32 v117, v2
	s_waitcnt vmcnt(3)
	v_mov_b32_e32 v134, v2
	s_waitcnt vmcnt(0)
	v_mov_b32_e32 v135, v2
	v_mov_b32_e32 v136, v2
	v_mov_b32_e32 v137, v2
	v_mov_b32_e32 v138, v2
	v_mov_b32_e32 v139, v2
	v_mov_b32_e32 v140, v2
	v_mov_b32_e32 v141, v2
	.p2alignl 6, 3212836864

; template <class Epi, class Sched, bool ALIGN_EPI>
; __device__ __forceinline__ void gemm_phase(LAS unsigned char* lds, const Gemm g, const Sched& S, const Epi& E) {
;     ...
;         const bool has_next = S.next(ui + 1, nxt);
;         const char* nA = has_next ? (const char*)g.A + (size_t)nxt.pm * tstepA + (size_t)nxt.pn * g.a_koff * 2 : cA; const char* nB = has_next ? (const char*)g.Bt + (size_t)nxt.pn * tstepB : cB;
; #pragma unroll 1
;         for (int t = 0; t < nt; t += 2) {
;             const bool last = (t == nt - 2);
;             const char* a1 = cA + (size_t)(t + 1) * kstep;
;             const char* a2 = last ? nA : cA + (size_t)(t + 2) * kstep; const char* b2 = last ? nB : cB + (size_t)(t + 2) * kstep;
;             const char* a3 = a2 + kstep; const char* b3 = b2 + kstep;
;             PG8_LDB(B0, 0, 0); PG8_LDB(B1, 0, 1); PG8_SCHED; PG8_LDA(At, 0, 0); PG8_STAGE(PG8_SA(1, 1), a1 + hstepA, voffA);
;             PG8_WAIT_V(8); PG8_WAIT_L(0); PG8_BAR; PG8_MMA(0, 0, At, B0); PG8_MMA(0, 1, At, B1); PG8_BAR; PG8_SCHED;
;             PG8_LDA(At, 0, 1); PG8_STAGE(PG8_SB(0, 0), b2, voffB); PG8_STAGE(PG8_SB(0, 1), b2 + hstepB, voffB); PG8_STAGE(PG8_SA(0, 0), a2, voffA);
;             PG8_WAIT_V(8); PG8_WAIT_L(0); PG8_BAR; PG8_MMA(1, 0, At, B0); PG8_MMA(1, 1, At, B1); PG8_BAR; PG8_SCHED;
;             PG8_LDB(B0, 1, 0); PG8_LDB(B1, 1, 1); PG8_SCHED; PG8_LDA(At, 1, 0); PG8_STAGE(PG8_SA(0, 1), a2 + hstepA, voffA);
;             PG8_WAIT_V(8); PG8_WAIT_L(0); PG8_BAR; PG8_MMA(0, 0, At, B0); PG8_MMA(0, 1, At, B1); PG8_BAR; PG8_SCHED;
;             PG8_LDA(At, 1, 1); PG8_STAGE(PG8_SB(1, 0), b3, voffB); PG8_STAGE(PG8_SB(1, 1), b3 + hstepB, voffB); PG8_STAGE(PG8_SA(1, 0), a3, voffA);
;             PG8_WAIT_V(8); PG8_WAIT_L(0); PG8_BAR; PG8_MMA(1, 0, At, B0); PG8_MMA(1, 1, At, B1); PG8_BAR; PG8_SCHED;
;         }
;         if constexpr (ALIGN_EPI) { if (wr == 0) PG8_BAR; }
;         if constexpr (Epi::NPRE > 0) E(acc, cur, wr, wc, fr, fq, pre); else
;         if constexpr (!Epi::AFTER_DRAIN) E(acc, cur, wr, wc, fr, fq);
;         if (!has_next) break;
; #pragma unroll
;         for (int a = 0; a < 2; ++a)
; #pragma unroll
;             for (int b = 0; b < 2; ++b)
; #pragma unroll
;                 for (int m = 0; m < 4; ++m)
; #pragma unroll
;                     for (int n = 0; n < 2; ++n) acc[a][b][m][n] = (f32x4){0.f, 0.f, 0.f, 0.f};
.LBB0_1408:
	s_mov_b32 s38, s6
	s_ashr_i32 s39, s6, 31
	s_mov_b32 s36, s2
	s_lshl_b64 s[2:3], s[38:39], 20
	s_add_u32 s40, s48, s2
	s_addc_u32 s41, s49, s3
	s_and_b64 s[2:3], s[44:45], exec
	s_cselect_b32 s2, s41, s5
	s_cselect_b32 s3, s40, s4
	s_ashr_i32 s37, s36, 31
	s_lshl_b64 s[6:7], s[36:37], 20
	s_add_u32 s42, s50, s6
	s_addc_u32 s43, s51, s7
	s_and_b64 s[6:7], s[44:45], exec
	s_cselect_b32 s6, s43, s9
	s_cselect_b32 s7, s42, s8
	s_add_u32 s23, s8, 0x100
	v_mov_b32_e32 v2, 0
	s_addc_u32 s37, s9, 0
	s_mov_b32 s39, -2
	v_mov_b32_e32 v3, v2
	v_mov_b32_e32 v4, v2
	v_mov_b32_e32 v5, v2
	v_mov_b32_e32 v6, v2
	v_mov_b32_e32 v7, v2
	v_mov_b32_e32 v8, v2
	v_mov_b32_e32 v9, v2
	v_mov_b32_e32 v18, v2
	v_mov_b32_e32 v19, v2
	v_mov_b32_e32 v20, v2
	v_mov_b32_e32 v21, v2
	v_mov_b32_e32 v22, v2
	v_mov_b32_e32 v23, v2
	v_mov_b32_e32 v24, v2
	v_mov_b32_e32 v25, v2
	v_mov_b32_e32 v34, v2
	v_mov_b32_e32 v35, v2
	v_mov_b32_e32 v36, v2
	v_mov_b32_e32 v37, v2
	v_mov_b32_e32 v38, v2
	v_mov_b32_e32 v39, v2
	v_mov_b32_e32 v40, v2
	v_mov_b32_e32 v41, v2
	v_mov_b32_e32 v50, v2
	v_mov_b32_e32 v51, v2
	v_mov_b32_e32 v52, v2
	v_mov_b32_e32 v53, v2
	v_mov_b32_e32 v54, v2
	v_mov_b32_e32 v55, v2
	v_mov_b32_e32 v56, v2
	v_mov_b32_e32 v57, v2
	v_mov_b32_e32 v10, v2
	v_mov_b32_e32 v11, v2
	v_mov_b32_e32 v12, v2
	v_mov_b32_e32 v13, v2
	v_mov_b32_e32 v14, v2
	v_mov_b32_e32 v15, v2
	v_mov_b32_e32 v16, v2
	v_mov_b32_e32 v17, v2
	v_mov_b32_e32 v26, v2
	v_mov_b32_e32 v27, v2
	v_mov_b32_e32 v28, v2
	v_mov_b32_e32 v29, v2
	v_mov_b32_e32 v30, v2
	v_mov_b32_e32 v31, v2
	v_mov_b32_e32 v32, v2
	v_mov_b32_e32 v33, v2
	v_mov_b32_e32 v42, v2
	v_mov_b32_e32 v43, v2
	v_mov_b32_e32 v44, v2
	v_mov_b32_e32 v45, v2
	v_mov_b32_e32 v46, v2
	v_mov_b32_e32 v47, v2
	v_mov_b32_e32 v48, v2
	v_mov_b32_e32 v49, v2
	v_mov_b32_e32 v58, v2
	v_mov_b32_e32 v59, v2
	v_mov_b32_e32 v60, v2
	v_mov_b32_e32 v61, v2
	v_mov_b32_e32 v62, v2
	v_mov_b32_e32 v63, v2
	v_mov_b32_e32 v64, v2
	v_mov_b32_e32 v65, v2
	v_mov_b32_e32 v66, v2
	v_mov_b32_e32 v67, v2
	v_mov_b32_e32 v68, v2
	v_mov_b32_e32 v69, v2
	v_mov_b32_e32 v70, v2
	v_mov_b32_e32 v71, v2
	v_mov_b32_e32 v72, v2
	v_mov_b32_e32 v73, v2
	v_mov_b32_e32 v82, v2
	v_mov_b32_e32 v83, v2
	v_mov_b32_e32 v84, v2
	v_mov_b32_e32 v85, v2
	v_mov_b32_e32 v86, v2
	v_mov_b32_e32 v87, v2
	v_mov_b32_e32 v88, v2
	v_mov_b32_e32 v89, v2
	v_mov_b32_e32 v98, v2
	v_mov_b32_e32 v99, v2
	v_mov_b32_e32 v100, v2
	v_mov_b32_e32 v101, v2
	v_mov_b32_e32 v102, v2
	v_mov_b32_e32 v103, v2
	v_mov_b32_e32 v104, v2
	v_mov_b32_e32 v105, v2
	v_mov_b32_e32 v114, v2
	v_mov_b32_e32 v115, v2
	v_mov_b32_e32 v116, v2
	v_mov_b32_e32 v117, v2
	v_mov_b32_e32 v118, v2
	v_mov_b32_e32 v119, v2
	v_mov_b32_e32 v120, v2
	v_mov_b32_e32 v121, v2
	v_mov_b32_e32 v74, v2
	v_mov_b32_e32 v75, v2
	v_mov_b32_e32 v76, v2
	v_mov_b32_e32 v77, v2
	v_mov_b32_e32 v78, v2
	v_mov_b32_e32 v79, v2
	v_mov_b32_e32 v80, v2
	v_mov_b32_e32 v81, v2
	v_mov_b32_e32 v90, v2
	v_mov_b32_e32 v91, v2
	v_mov_b32_e32 v92, v2
	v_mov_b32_e32 v93, v2
	v_mov_b32_e32 v94, v2
	v_mov_b32_e32 v95, v2
	v_mov_b32_e32 v96, v2
	v_mov_b32_e32 v97, v2
	v_mov_b32_e32 v106, v2
	v_mov_b32_e32 v107, v2
	v_mov_b32_e32 v108, v2
	v_mov_b32_e32 v109, v2
	v_mov_b32_e32 v110, v2
	v_mov_b32_e32 v111, v2
	v_mov_b32_e32 v112, v2
	v_mov_b32_e32 v113, v2
	v_mov_b32_e32 v122, v2
	v_mov_b32_e32 v123, v2
	v_mov_b32_e32 v124, v2
	v_mov_b32_e32 v125, v2
	v_mov_b32_e32 v126, v2
	v_mov_b32_e32 v127, v2
	v_mov_b32_e32 v128, v2
	v_mov_b32_e32 v129, v2
	.p2alignl 6, 3212836864

; template <class Epi, class Sched, bool ALIGN_EPI>
; __device__ __forceinline__ void gemm_phase(LAS unsigned char* lds, const Gemm g, const Sched& S, const Epi& E) {
;     ...
;         const bool has_next = S.next(ui + 1, nxt);
;         const char* nA = has_next ? (const char*)g.A + (size_t)nxt.pm * tstepA + (size_t)nxt.pn * g.a_koff * 2 : cA; const char* nB = has_next ? (const char*)g.Bt + (size_t)nxt.pn * tstepB : cB;
; #pragma unroll 1
;         for (int t = 0; t < nt; t += 2) {
;             const bool last = (t == nt - 2);
;             const char* a1 = cA + (size_t)(t + 1) * kstep;
;             const char* a2 = last ? nA : cA + (size_t)(t + 2) * kstep; const char* b2 = last ? nB : cB + (size_t)(t + 2) * kstep;
;             const char* a3 = a2 + kstep; const char* b3 = b2 + kstep;
;             PG8_LDB(B0, 0, 0); PG8_LDB(B1, 0, 1); PG8_SCHED; PG8_LDA(At, 0, 0); PG8_STAGE(PG8_SA(1, 1), a1 + hstepA, voffA);
;             PG8_WAIT_V(8); PG8_WAIT_L(0); PG8_BAR; PG8_MMA(0, 0, At, B0); PG8_MMA(0, 1, At, B1); PG8_BAR; PG8_SCHED;
;             PG8_LDA(At, 0, 1); PG8_STAGE(PG8_SB(0, 0), b2, voffB); PG8_STAGE(PG8_SB(0, 1), b2 + hstepB, voffB); PG8_STAGE(PG8_SA(0, 0), a2, voffA);
;             PG8_WAIT_V(8); PG8_WAIT_L(0); PG8_BAR; PG8_MMA(1, 0, At, B0); PG8_MMA(1, 1, At, B1); PG8_BAR; PG8_SCHED;
;             PG8_LDB(B0, 1, 0); PG8_LDB(B1, 1, 1); PG8_SCHED; PG8_LDA(At, 1, 0); PG8_STAGE(PG8_SA(0, 1), a2 + hstepA, voffA);
;             PG8_WAIT_V(8); PG8_WAIT_L(0); PG8_BAR; PG8_MMA(0, 0, At, B0); PG8_MMA(0, 1, At, B1); PG8_BAR; PG8_SCHED;
;             PG8_LDA(At, 1, 1); PG8_STAGE(PG8_SB(1, 0), b3, voffB); PG8_STAGE(PG8_SB(1, 1), b3 + hstepB, voffB); PG8_STAGE(PG8_SA(1, 0), a3, voffA);
;             PG8_WAIT_V(8); PG8_WAIT_L(0); PG8_BAR; PG8_MMA(1, 0, At, B0); PG8_MMA(1, 1, At, B1); PG8_BAR; PG8_SCHED;
;         }
;         if constexpr (ALIGN_EPI) { if (wr == 0) PG8_BAR; }
;         if constexpr (Epi::NPRE > 0) E(acc, cur, wr, wc, fr, fq, pre); else
;         if constexpr (!Epi::AFTER_DRAIN) E(acc, cur, wr, wc, fr, fq);
;         if (!has_next) break;
; #pragma unroll
;         for (int a = 0; a < 2; ++a)
; #pragma unroll
;             for (int b = 0; b < 2; ++b)
; #pragma unroll
;                 for (int m = 0; m < 4; ++m)
; #pragma unroll
;                     for (int n = 0; n < 2; ++n) acc[a][b][m][n] = (f32x4){0.f, 0.f, 0.f, 0.f};
.LBB0_1993:
	s_ashr_i32 s21, s20, 31
	s_lshl_b64 s[6:7], s[20:21], 20
	s_add_u32 s22, s36, s6
	s_addc_u32 s23, s37, s7
	s_and_b64 s[6:7], s[12:13], exec
	s_cselect_b32 s3, s23, s29
	s_cselect_b32 s5, s22, s28
	s_ashr_i32 s19, s18, 31
	s_lshl_b64 s[6:7], s[18:19], 20
	s_add_u32 s24, s38, s6
	s_addc_u32 s25, s39, s7
	s_and_b64 s[6:7], s[12:13], exec
	s_cselect_b32 s6, s25, s27
	s_cselect_b32 s7, s24, s26
	s_add_u32 s19, s28, 0x100
	s_addc_u32 s21, s29, 0
	s_add_u32 s57, s26, 0x100
	s_addc_u32 s58, s27, 0
	s_add_u32 s26, s28, 0x80080
	v_mov_b32_e32 v2, 0
	s_addc_u32 s27, s29, 0
	s_mov_b32 s59, -2
	s_waitcnt lgkmcnt(0)
	v_mov_b32_e32 v3, v2
	v_mov_b32_e32 v4, v2
	v_mov_b32_e32 v5, v2
	v_mov_b32_e32 v6, v2
	v_mov_b32_e32 v7, v2
	v_mov_b32_e32 v8, v2
	v_mov_b32_e32 v9, v2
	v_mov_b32_e32 v18, v2
	v_mov_b32_e32 v19, v2
	v_mov_b32_e32 v20, v2
	v_mov_b32_e32 v21, v2
	v_mov_b32_e32 v22, v2
	v_mov_b32_e32 v23, v2
	v_mov_b32_e32 v24, v2
	v_mov_b32_e32 v25, v2
	v_mov_b32_e32 v34, v2
	v_mov_b32_e32 v35, v2
	v_mov_b32_e32 v36, v2
	v_mov_b32_e32 v37, v2
	v_mov_b32_e32 v38, v2
	v_mov_b32_e32 v39, v2
	v_mov_b32_e32 v40, v2
	v_mov_b32_e32 v41, v2
	v_mov_b32_e32 v50, v2
	v_mov_b32_e32 v51, v2
	v_mov_b32_e32 v52, v2
	v_mov_b32_e32 v53, v2
	v_mov_b32_e32 v54, v2
	v_mov_b32_e32 v55, v2
	v_mov_b32_e32 v56, v2
	v_mov_b32_e32 v57, v2
	v_mov_b32_e32 v10, v2
	v_mov_b32_e32 v11, v2
	v_mov_b32_e32 v12, v2
	v_mov_b32_e32 v13, v2
	v_mov_b32_e32 v14, v2
	v_mov_b32_e32 v15, v2
	v_mov_b32_e32 v16, v2
	v_mov_b32_e32 v17, v2
	v_mov_b32_e32 v26, v2
	v_mov_b32_e32 v27, v2
	v_mov_b32_e32 v28, v2
	v_mov_b32_e32 v29, v2
	v_mov_b32_e32 v30, v2
	v_mov_b32_e32 v31, v2
	v_mov_b32_e32 v32, v2
	v_mov_b32_e32 v33, v2
	v_mov_b32_e32 v42, v2
	v_mov_b32_e32 v43, v2
	v_mov_b32_e32 v44, v2
	v_mov_b32_e32 v45, v2
	v_mov_b32_e32 v46, v2
	v_mov_b32_e32 v47, v2
	v_mov_b32_e32 v48, v2
	v_mov_b32_e32 v49, v2
	v_mov_b32_e32 v58, v2
	v_mov_b32_e32 v59, v2
	v_mov_b32_e32 v60, v2
	v_mov_b32_e32 v61, v2
	v_mov_b32_e32 v62, v2
	v_mov_b32_e32 v63, v2
	v_mov_b32_e32 v64, v2
	v_mov_b32_e32 v65, v2
	v_mov_b32_e32 v66, v2
	v_mov_b32_e32 v67, v2
	v_mov_b32_e32 v68, v2
	v_mov_b32_e32 v69, v2
	v_mov_b32_e32 v70, v2
	v_mov_b32_e32 v71, v2
	v_mov_b32_e32 v72, v2
	v_mov_b32_e32 v73, v2
	v_mov_b32_e32 v82, v2
	v_mov_b32_e32 v83, v2
	v_mov_b32_e32 v84, v2
	v_mov_b32_e32 v85, v2
	v_mov_b32_e32 v86, v2
	v_mov_b32_e32 v87, v2
	v_mov_b32_e32 v88, v2
	v_mov_b32_e32 v89, v2
	s_waitcnt vmcnt(11)
	v_mov_b32_e32 v98, v2
	v_mov_b32_e32 v99, v2
	v_mov_b32_e32 v100, v2
	v_mov_b32_e32 v101, v2
	s_waitcnt vmcnt(10)
	v_mov_b32_e32 v102, v2
	v_mov_b32_e32 v103, v2
	v_mov_b32_e32 v104, v2
	v_mov_b32_e32 v105, v2
	s_waitcnt vmcnt(6)
	v_mov_b32_e32 v118, v2
	v_mov_b32_e32 v119, v2
	v_mov_b32_e32 v120, v2
	v_mov_b32_e32 v121, v2
	s_waitcnt vmcnt(5)
	v_mov_b32_e32 v122, v2
	v_mov_b32_e32 v123, v2
	v_mov_b32_e32 v124, v2
	v_mov_b32_e32 v125, v2
	v_mov_b32_e32 v74, v2
	v_mov_b32_e32 v75, v2
	v_mov_b32_e32 v76, v2
	v_mov_b32_e32 v77, v2
	v_mov_b32_e32 v78, v2
	v_mov_b32_e32 v79, v2
	v_mov_b32_e32 v80, v2
	v_mov_b32_e32 v81, v2
	v_mov_b32_e32 v90, v2
	v_mov_b32_e32 v91, v2
	v_mov_b32_e32 v92, v2
	v_mov_b32_e32 v93, v2
	v_mov_b32_e32 v94, v2
	v_mov_b32_e32 v95, v2
	v_mov_b32_e32 v96, v2
	v_mov_b32_e32 v97, v2
	v_mov_b32_e32 v106, v2
	v_mov_b32_e32 v107, v2
	v_mov_b32_e32 v108, v2
	v_mov_b32_e32 v109, v2
	v_mov_b32_e32 v114, v2
	v_mov_b32_e32 v115, v2
	v_mov_b32_e32 v116, v2
	v_mov_b32_e32 v117, v2
	s_waitcnt vmcnt(2)
	v_mov_b32_e32 v134, v2
	s_waitcnt vmcnt(0)
	v_mov_b32_e32 v135, v2
	v_mov_b32_e32 v136, v2
	v_mov_b32_e32 v137, v2
	v_mov_b32_e32 v138, v2
	v_mov_b32_e32 v139, v2
	v_mov_b32_e32 v140, v2
	v_mov_b32_e32 v141, v2
	.p2alignl 6, 3212836864

; template <class Epi, class Sched, bool ALIGN_EPI>
; __device__ __forceinline__ void gemm_phase(LAS unsigned char* lds, const Gemm g, const Sched& S, const Epi& E) {
;     ...
;         const bool has_next = S.next(ui + 1, nxt);
;         const char* nA = has_next ? (const char*)g.A + (size_t)nxt.pm * tstepA + (size_t)nxt.pn * g.a_koff * 2 : cA; const char* nB = has_next ? (const char*)g.Bt + (size_t)nxt.pn * tstepB : cB;
; #pragma unroll 1
;         for (int t = 0; t < nt; t += 2) {
;             const bool last = (t == nt - 2);
;             const char* a1 = cA + (size_t)(t + 1) * kstep;
;             const char* a2 = last ? nA : cA + (size_t)(t + 2) * kstep; const char* b2 = last ? nB : cB + (size_t)(t + 2) * kstep;
;             const char* a3 = a2 + kstep; const char* b3 = b2 + kstep;
;             PG8_LDB(B0, 0, 0); PG8_LDB(B1, 0, 1); PG8_SCHED; PG8_LDA(At, 0, 0); PG8_STAGE(PG8_SA(1, 1), a1 + hstepA, voffA);
;             PG8_WAIT_V(8); PG8_WAIT_L(0); PG8_BAR; PG8_MMA(0, 0, At, B0); PG8_MMA(0, 1, At, B1); PG8_BAR; PG8_SCHED;
;             PG8_LDA(At, 0, 1); PG8_STAGE(PG8_SB(0, 0), b2, voffB); PG8_STAGE(PG8_SB(0, 1), b2 + hstepB, voffB); PG8_STAGE(PG8_SA(0, 0), a2, voffA);
;             PG8_WAIT_V(8); PG8_WAIT_L(0); PG8_BAR; PG8_MMA(1, 0, At, B0); PG8_MMA(1, 1, At, B1); PG8_BAR; PG8_SCHED;
;             PG8_LDB(B0, 1, 0); PG8_LDB(B1, 1, 1); PG8_SCHED; PG8_LDA(At, 1, 0); PG8_STAGE(PG8_SA(0, 1), a2 + hstepA, voffA);
;             PG8_WAIT_V(8); PG8_WAIT_L(0); PG8_BAR; PG8_MMA(0, 0, At, B0); PG8_MMA(0, 1, At, B1); PG8_BAR; PG8_SCHED;
;             PG8_LDA(At, 1, 1); PG8_STAGE(PG8_SB(1, 0), b3, voffB); PG8_STAGE(PG8_SB(1, 1), b3 + hstepB, voffB); PG8_STAGE(PG8_SA(1, 0), a3, voffA);
;             PG8_WAIT_V(8); PG8_WAIT_L(0); PG8_BAR; PG8_MMA(1, 0, At, B0); PG8_MMA(1, 1, At, B1); PG8_BAR; PG8_SCHED;
;         }
;         if constexpr (ALIGN_EPI) { if (wr == 0) PG8_BAR; }
;         if constexpr (Epi::NPRE > 0) E(acc, cur, wr, wc, fr, fq, pre); else
;         if constexpr (!Epi::AFTER_DRAIN) E(acc, cur, wr, wc, fr, fq);
;         if (!has_next) break;
; #pragma unroll
;         for (int a = 0; a < 2; ++a)
; #pragma unroll
;             for (int b = 0; b < 2; ++b)
; #pragma unroll
;                 for (int m = 0; m < 4; ++m)
; #pragma unroll
;                     for (int n = 0; n < 2; ++n) acc[a][b][m][n] = (f32x4){0.f, 0.f, 0.f, 0.f};
.LBB0_2074:
	s_ashr_i32 s21, s20, 31
	s_lshl_b64 s[6:7], s[20:21], 20
	s_add_u32 s22, s38, s6
	s_addc_u32 s23, s39, s7
	s_and_b64 s[6:7], s[10:11], exec
	s_cselect_b32 s3, s23, s27
	s_cselect_b32 s5, s22, s26
	s_ashr_i32 s19, s18, 31
	s_lshl_b64 s[6:7], s[18:19], 20
	s_add_u32 s24, s40, s6
	s_addc_u32 s25, s41, s7
	s_and_b64 s[6:7], s[10:11], exec
	s_cselect_b32 s6, s25, s29
	s_cselect_b32 s7, s24, s28
	s_add_u32 s19, s28, 0x100
	v_mov_b32_e32 v2, 0
	s_addc_u32 s21, s29, 0
	s_mov_b32 s60, -2
	v_mov_b32_e32 v3, v2
	v_mov_b32_e32 v4, v2
	v_mov_b32_e32 v5, v2
	v_mov_b32_e32 v6, v2
	v_mov_b32_e32 v7, v2
	v_mov_b32_e32 v8, v2
	v_mov_b32_e32 v9, v2
	v_mov_b32_e32 v18, v2
	v_mov_b32_e32 v19, v2
	v_mov_b32_e32 v20, v2
	v_mov_b32_e32 v21, v2
	v_mov_b32_e32 v22, v2
	v_mov_b32_e32 v23, v2
	v_mov_b32_e32 v24, v2
	v_mov_b32_e32 v25, v2
	v_mov_b32_e32 v34, v2
	v_mov_b32_e32 v35, v2
	v_mov_b32_e32 v36, v2
	v_mov_b32_e32 v37, v2
	v_mov_b32_e32 v38, v2
	v_mov_b32_e32 v39, v2
	v_mov_b32_e32 v40, v2
	v_mov_b32_e32 v41, v2
	v_mov_b32_e32 v50, v2
	v_mov_b32_e32 v51, v2
	v_mov_b32_e32 v52, v2
	v_mov_b32_e32 v53, v2
	v_mov_b32_e32 v54, v2
	v_mov_b32_e32 v55, v2
	v_mov_b32_e32 v56, v2
	v_mov_b32_e32 v57, v2
	v_mov_b32_e32 v10, v2
	v_mov_b32_e32 v11, v2
	v_mov_b32_e32 v12, v2
	v_mov_b32_e32 v13, v2
	v_mov_b32_e32 v14, v2
	v_mov_b32_e32 v15, v2
	v_mov_b32_e32 v16, v2
	v_mov_b32_e32 v17, v2
	v_mov_b32_e32 v26, v2
	v_mov_b32_e32 v27, v2
	v_mov_b32_e32 v28, v2
	v_mov_b32_e32 v29, v2
	v_mov_b32_e32 v30, v2
	v_mov_b32_e32 v31, v2
	v_mov_b32_e32 v32, v2
	v_mov_b32_e32 v33, v2
	v_mov_b32_e32 v42, v2
	v_mov_b32_e32 v43, v2
	v_mov_b32_e32 v44, v2
	v_mov_b32_e32 v45, v2
	v_mov_b32_e32 v46, v2
	v_mov_b32_e32 v47, v2
	v_mov_b32_e32 v48, v2
	v_mov_b32_e32 v49, v2
	v_mov_b32_e32 v58, v2
	v_mov_b32_e32 v59, v2
	v_mov_b32_e32 v60, v2
	v_mov_b32_e32 v61, v2
	v_mov_b32_e32 v62, v2
	v_mov_b32_e32 v63, v2
	v_mov_b32_e32 v64, v2
	v_mov_b32_e32 v65, v2
	v_mov_b32_e32 v66, v2
	v_mov_b32_e32 v67, v2
	v_mov_b32_e32 v68, v2
	v_mov_b32_e32 v69, v2
	v_mov_b32_e32 v70, v2
	v_mov_b32_e32 v71, v2
	v_mov_b32_e32 v72, v2
	v_mov_b32_e32 v73, v2
	v_mov_b32_e32 v82, v2
	v_mov_b32_e32 v83, v2
	v_mov_b32_e32 v84, v2
	v_mov_b32_e32 v85, v2
	v_mov_b32_e32 v86, v2
	v_mov_b32_e32 v87, v2
	v_mov_b32_e32 v88, v2
	v_mov_b32_e32 v89, v2
	v_mov_b32_e32 v98, v2
	v_mov_b32_e32 v99, v2
	v_mov_b32_e32 v100, v2
	v_mov_b32_e32 v101, v2
	v_mov_b32_e32 v102, v2
	v_mov_b32_e32 v103, v2
	v_mov_b32_e32 v104, v2
	v_mov_b32_e32 v105, v2
	v_mov_b32_e32 v114, v2
	v_mov_b32_e32 v115, v2
	v_mov_b32_e32 v116, v2
	v_mov_b32_e32 v117, v2
	v_mov_b32_e32 v118, v2
	v_mov_b32_e32 v119, v2
	v_mov_b32_e32 v120, v2
	v_mov_b32_e32 v121, v2
	v_mov_b32_e32 v74, v2
	v_mov_b32_e32 v75, v2
	v_mov_b32_e32 v76, v2
	v_mov_b32_e32 v77, v2
	v_mov_b32_e32 v78, v2
	v_mov_b32_e32 v79, v2
	v_mov_b32_e32 v80, v2
	v_mov_b32_e32 v81, v2
	v_mov_b32_e32 v90, v2
	v_mov_b32_e32 v91, v2
	v_mov_b32_e32 v92, v2
	v_mov_b32_e32 v93, v2
	v_mov_b32_e32 v94, v2
	v_mov_b32_e32 v95, v2
	v_mov_b32_e32 v96, v2
	v_mov_b32_e32 v97, v2
	v_mov_b32_e32 v106, v2
	v_mov_b32_e32 v107, v2
	v_mov_b32_e32 v108, v2
	v_mov_b32_e32 v109, v2
	v_mov_b32_e32 v110, v2
	v_mov_b32_e32 v111, v2
	v_mov_b32_e32 v112, v2
	v_mov_b32_e32 v113, v2
	v_mov_b32_e32 v122, v2
	v_mov_b32_e32 v123, v2
	v_mov_b32_e32 v124, v2
	v_mov_b32_e32 v125, v2
	v_mov_b32_e32 v126, v2
	v_mov_b32_e32 v127, v2
	v_mov_b32_e32 v128, v2
	v_mov_b32_e32 v129, v2
	.p2alignl 6, 3212836864

; template <class Epi, class Sched, bool ALIGN_EPI>
; __device__ __forceinline__ void gemm_phase(LAS unsigned char* lds, const Gemm g, const Sched& S, const Epi& E) {
;     ...
;         for (int t = 0; t < nt; t += 2) {
;             const bool last = (t == nt - 2);
.LBB0_2171:
	s_mov_b32 s60, -2
	s_mov_b64 s[26:27], 0
	.p2alignl 6, 3212836864
